# next item's index-query/head-weight rows touched by wave 0 after its indexer loop (queue atomic moved to item start) so the next item's operand loads hit L2
# speedup vs baseline: 1.0056x; 1.0056x over previous
; #define TILE_LOAD(SLOT, CC, TT) do { const bf16_t* kp = P.KI + (rowb + 64 * (CC) + 16 * (TT) + r16) * 64 + 8 * g; Bk[SLOT][0] = *(const bf16x8*)kp; Bk[SLOT][1] = *(const bf16x8*)(kp + 32); } while (0)
; #define TILE_MATH(SLOT, TT) do { _Pragma("unroll") for (int q = 0; q < 4; ++q) { f32x4 a = {0.f, 0.f, 0.f, 0.f}; \
;             a = mfma16(Aq[q][0], Bk[SLOT][0], a); a = mfma16(Aq[q][1], Bk[SLOT][1], a); \
;             pv[q][TT] = wq[q][0] * fmaxf(a[0], 0.f) + wq[q][1] * fmaxf(a[1], 0.f) + wq[q][2] * fmaxf(a[2], 0.f) + wq[q][3] * fmaxf(a[3], 0.f); } } while (0)
; __device__ __forceinline__ void attn_item(const Ptrs& P, unsigned char* lds, int b, int tq0, int tid) {
;     ...
;         for (int q = 0; q < 4; ++q) { const bf16_t* qp = P.QI + (rowb + tq0 + q) * 1024 + r16 * 64 + 8 * g; Aq[q][0] = *(const bf16x8*)qp; Aq[q][1] = *(const bf16x8*)(qp + 32);
;             wq[q] = *(const f32x4*)(P.WI + (rowb + tq0 + q) * 16 + 4 * g); }
;         unsigned* KB = (unsigned*)lds;
;         const int nch = (tmax >> 6) + 1;
;         const int ni = (w < nch) ? ((nch - w + 7) >> 3) : 0;
;         bf16x8 Bk[4][2];
;     ...
;         if (ni > 0) { TILE_LOAD(0, w, 0); TILE_LOAD(1, w, 1); }
; #pragma unroll 1
;         for (int it = 0; it < ni; ++it) {
;             const int c = 8 * it + w; const bool more = it + 1 < ni;
;             float pv[4][4], sv[4];
;             TILE_LOAD(2, c, 2); TILE_MATH(0, 0);
;             TILE_LOAD(3, c, 3); TILE_MATH(1, 1);
;             if (more) TILE_LOAD(0, c + 8, 0);
;             TILE_MATH(2, 2);
; __global__ void __launch_bounds__(512, 2) mega_fwd(Args args) {
;     ...
;                 if (tid == 0) *(volatile int*)(lds + 147712) = (int)atomicAdd(ctl + 64 * b, 1u);
.Lq_have_item:
	s_movk_i32 s12, 0x800
	s_waitcnt lgkmcnt(0)
	v_cmp_gt_i32_e32 vcc, s12, v0
	s_mov_b64 s[12:13], -1
	s_and_saveexec_b64 s[70:71], vcc
	s_cbranch_execz .LBB0_465
	s_and_saveexec_b64 s[90:91], s[0:1]
	v_mov_b32_e32 v255, 1
	global_atomic_add v254, v165, v255, s[46:47] sc0
	s_mov_b64 exec, s[90:91]
	s_nop 0
	s_nop 0
	s_nop 0
	s_nop 0
	s_nop 0
	s_nop 0
	s_nop 0
	s_nop 0
	s_nop 0
	s_nop 0
	s_nop 0
	v_lshlrev_b32_e32 v64, 2, v0
	v_sub_u32_e32 v124, 0x1ffc, v64
	v_readfirstlane_b32 s63, v188
	s_movk_i32 s12, 0xfc
	s_lshr_b32 s62, s63, 6
	v_cmp_lt_u32_e32 vcc, s12, v124
	s_and_saveexec_b64 s[12:13], vcc
	s_xor_b64 s[60:61], exec, s[12:13]
	s_cbranch_execz .LBB0_913
	v_sub_u32_e32 v126, 0x1fff, v64
	v_lshrrev_b32_e32 v125, 6, v126
	v_subrev_u32_e32 v0, s62, v125
	v_add_u32_e32 v65, 8, v0
	v_cmp_le_u32_e32 vcc, s62, v125
	v_cmp_lt_u32_e64 s[12:13], 7, v65
	s_and_b64 s[14:15], vcc, s[12:13]
	s_and_saveexec_b64 s[12:13], s[14:15]
	s_cbranch_execz .LBB0_479
	s_and_b32 s14, s63, 0xffffffc0
	v_add_u32_e32 v164, s81, v124
	s_ashr_i32 s15, s14, 31
	v_or_b32_e32 v40, 1, v164
	v_mov_b32_e32 v41, v165
	v_or_b32_e32 v32, 2, v164
	v_mov_b32_e32 v33, v165
	v_or_b32_e32 v34, 3, v164
	v_mov_b32_e32 v35, v165
	v_lshl_add_u64 v[48:49], s[14:15], 0, v[182:183]
	v_lshlrev_b64 v[0:1], 11, v[164:165]
	v_lshlrev_b64 v[8:9], 11, v[40:41]
	v_lshlrev_b64 v[16:17], 11, v[32:33]
	v_lshlrev_b64 v[24:25], 11, v[34:35]
	v_lshlrev_b64 v[34:35], 6, v[34:35]
	v_lshlrev_b64 v[32:33], 6, v[32:33]
	v_lshlrev_b64 v[40:41], 6, v[40:41]
	v_lshlrev_b64 v[42:43], 6, v[164:165]
	v_lshlrev_b64 v[48:49], 7, v[48:49]
	v_lshl_add_u64 v[4:5], v[168:169], 0, v[0:1]
	v_lshl_add_u64 v[12:13], v[168:169], 0, v[8:9]
	v_lshl_add_u64 v[20:21], v[168:169], 0, v[16:17]
	v_lshl_add_u64 v[28:29], v[168:169], 0, v[24:25]
	v_lshl_add_u64 v[34:35], v[170:171], 0, v[34:35]
	v_lshl_add_u64 v[36:37], v[170:171], 0, v[32:33]
	v_lshl_add_u64 v[40:41], v[170:171], 0, v[40:41]
	v_lshl_add_u64 v[44:45], v[170:171], 0, v[42:43]
	v_lshl_add_u64 v[60:61], v[172:173], 0, v[48:49]
	global_load_dwordx4 v[0:3], v[4:5], off
	s_nop 0
	global_load_dwordx4 v[4:7], v[4:5], off offset:64
	s_nop 0
	global_load_dwordx4 v[8:11], v[12:13], off
	s_nop 0
	global_load_dwordx4 v[12:15], v[12:13], off offset:64
	s_nop 0
	global_load_dwordx4 v[16:19], v[20:21], off
	s_nop 0
	global_load_dwordx4 v[20:23], v[20:21], off offset:64
	s_nop 0
	global_load_dwordx4 v[24:27], v[28:29], off
	s_nop 0
	global_load_dwordx4 v[28:31], v[28:29], off offset:64
	s_nop 0
	global_load_dwordx4 v[32:35], v[34:35], off
	s_nop 0
	global_load_dwordx4 v[36:39], v[36:37], off
	s_nop 0
	global_load_dwordx4 v[40:43], v[40:41], off
	s_nop 0
	global_load_dwordx4 v[44:47], v[44:45], off
	s_nop 0
	v_lshrrev_b32_e32 v127, 3, v65
	v_sub_u32_e32 v128, 0x1ffd, v64
	v_sub_u32_e32 v129, 0x1ffe, v64
	v_mov_b64_e32 v[150:151], v[60:61]
	s_mov_b64 s[18:19], 0x1000
	v_lshl_add_u64 v[152:153], v[60:61], 0, s[18:19]
	global_load_dwordx4 v[48:51], v[150:151], off
	global_load_dwordx4 v[52:55], v[150:151], off offset:1024
	global_load_dwordx4 v[56:59], v[150:151], off offset:2048
	global_load_dwordx4 v[60:63], v[150:151], off offset:3072
	global_load_dwordx4 v[64:67], v[152:153], off
	global_load_dwordx4 v[68:71], v[152:153], off offset:1024
	global_load_dwordx4 v[72:75], v[152:153], off offset:2048
	global_load_dwordx4 v[76:79], v[152:153], off offset:3072
	s_mov_b64 s[18:19], 0x10000
	v_lshl_add_u64 v[150:151], v[150:151], 0, s[18:19]
	v_lshl_add_u64 v[152:153], v[152:153], 0, s[18:19]
	s_mov_b32 s20, 0
	v_lshl_add_u32 v130, s62, 8, v203
	v_add_u32_e32 v155, 0x10000, v130
	v_add_u32_e32 v154, s14, v179
	s_nop 0
	v_readfirstlane_b32 s14, v127
.Lidx_loop:
	s_waitcnt vmcnt(6)
	v_mfma_f32_16x16x32_bf16 v[80:83], v[0:3], v[48:51], 0
	v_mfma_f32_16x16x32_bf16 v[84:87], v[8:11], v[48:51], 0
	v_mfma_f32_16x16x32_bf16 v[88:91], v[16:19], v[48:51], 0
	v_mfma_f32_16x16x32_bf16 v[92:95], v[24:27], v[48:51], 0
	v_mfma_f32_16x16x32_bf16 v[80:83], v[4:7], v[52:55], v[80:83]
	v_mfma_f32_16x16x32_bf16 v[84:87], v[12:15], v[52:55], v[84:87]
	v_mfma_f32_16x16x32_bf16 v[88:91], v[20:23], v[52:55], v[88:91]
	v_mfma_f32_16x16x32_bf16 v[92:95], v[28:31], v[52:55], v[92:95]
	global_load_dwordx4 v[48:51], v[150:151], off
	global_load_dwordx4 v[52:55], v[150:151], off offset:1024
	s_waitcnt vmcnt(6)
	v_mfma_f32_16x16x32_bf16 v[96:99], v[0:3], v[56:59], 0
	v_mfma_f32_16x16x32_bf16 v[100:103], v[8:11], v[56:59], 0
	v_mfma_f32_16x16x32_bf16 v[104:107], v[16:19], v[56:59], 0
	v_mfma_f32_16x16x32_bf16 v[108:111], v[24:27], v[56:59], 0
	v_mfma_f32_16x16x32_bf16 v[96:99], v[4:7], v[60:63], v[96:99]
	v_mfma_f32_16x16x32_bf16 v[100:103], v[12:15], v[60:63], v[100:103]
	v_mfma_f32_16x16x32_bf16 v[104:107], v[20:23], v[60:63], v[104:107]
	v_mfma_f32_16x16x32_bf16 v[108:111], v[28:31], v[60:63], v[108:111]
	global_load_dwordx4 v[56:59], v[150:151], off offset:2048
	global_load_dwordx4 v[60:63], v[150:151], off offset:3072
	v_max_f32_e32 v80, 0, v80
	v_max_f32_e32 v84, 0, v84
	v_max_f32_e32 v88, 0, v88
	v_max_f32_e32 v92, 0, v92
	v_max_f32_e32 v81, 0, v81
	v_max_f32_e32 v85, 0, v85
	v_max_f32_e32 v89, 0, v89
	v_max_f32_e32 v93, 0, v93
	v_max_f32_e32 v82, 0, v82
	v_max_f32_e32 v86, 0, v86
	v_max_f32_e32 v90, 0, v90
	v_max_f32_e32 v94, 0, v94
	v_max_f32_e32 v83, 0, v83
	v_max_f32_e32 v87, 0, v87
	v_max_f32_e32 v91, 0, v91
	v_max_f32_e32 v95, 0, v95
	v_mul_f32_e32 v132, v44, v80
	v_mul_f32_e32 v136, v40, v84
	v_mul_f32_e32 v140, v36, v88
	v_mul_f32_e32 v144, v32, v92
	v_fmac_f32_e32 v132, v45, v81
	v_fmac_f32_e32 v136, v41, v85
	v_fmac_f32_e32 v140, v37, v89
	v_fmac_f32_e32 v144, v33, v93
	v_fmac_f32_e32 v132, v46, v82
	v_fmac_f32_e32 v136, v42, v86
	v_fmac_f32_e32 v140, v38, v90
	v_fmac_f32_e32 v144, v34, v94
	v_fmac_f32_e32 v132, v47, v83
	v_fmac_f32_e32 v136, v43, v87
	v_fmac_f32_e32 v140, v39, v91
	v_fmac_f32_e32 v144, v35, v95
	s_waitcnt vmcnt(6)
; __device__ __forceinline__ unsigned f2key(float f) { const unsigned u = __builtin_bit_cast(unsigned, f); return (u & 0x80000000u) ? ~u : (u | 0x80000000u); }
; #define TILE_LOAD(SLOT, CC, TT) do { const bf16_t* kp = P.KI + (rowb + 64 * (CC) + 16 * (TT) + r16) * 64 + 8 * g; Bk[SLOT][0] = *(const bf16x8*)kp; Bk[SLOT][1] = *(const bf16x8*)(kp + 32); } while (0)
; #define TILE_MATH(SLOT, TT) do { _Pragma("unroll") for (int q = 0; q < 4; ++q) { f32x4 a = {0.f, 0.f, 0.f, 0.f}; \
;             a = mfma16(Aq[q][0], Bk[SLOT][0], a); a = mfma16(Aq[q][1], Bk[SLOT][1], a); \
;             pv[q][TT] = wq[q][0] * fmaxf(a[0], 0.f) + wq[q][1] * fmaxf(a[1], 0.f) + wq[q][2] * fmaxf(a[2], 0.f) + wq[q][3] * fmaxf(a[3], 0.f); } } while (0)
; __device__ __forceinline__ void attn_item(const Ptrs& P, unsigned char* lds, int b, int tq0, int tid) {
;     ...
;             TILE_LOAD(2, c, 2); TILE_MATH(0, 0);
;             TILE_LOAD(3, c, 3); TILE_MATH(1, 1);
;             if (more) TILE_LOAD(0, c + 8, 0);
;             TILE_MATH(2, 2);
;             if (more) TILE_LOAD(1, c + 8, 1);
;             TILE_MATH(3, 3);
; #pragma unroll
;             for (int q = 0; q < 4; ++q) { float a0 = pv[q][0], b0 = pv[q][2], a1 = pv[q][1], b1 = pv[q][3];
;                 asm("s_nop 1\n\tv_permlane32_swap_b32 %0, %1" : "+v"(a0), "+v"(b0));
;                 asm("s_nop 1\n\tv_permlane32_swap_b32 %0, %1" : "+v"(a1), "+v"(b1));
;                 float x = a0 + b0, y = a1 + b1;
;                 asm("s_nop 1\n\tv_permlane16_swap_b32 %0, %1" : "+v"(x), "+v"(y));
;                 sv[q] = x + y; }
;             const int s = 64 * c + lane;
; #pragma unroll
;             for (int q = 0; q < 4; ++q) KB[q * 8192 + s] = (s <= tq0 + q) ? f2key(sv[q]) : 0u;
	v_mfma_f32_16x16x32_bf16 v[80:83], v[0:3], v[64:67], 0
	v_mfma_f32_16x16x32_bf16 v[84:87], v[8:11], v[64:67], 0
	v_mfma_f32_16x16x32_bf16 v[88:91], v[16:19], v[64:67], 0
	v_mfma_f32_16x16x32_bf16 v[92:95], v[24:27], v[64:67], 0
	v_mfma_f32_16x16x32_bf16 v[80:83], v[4:7], v[68:71], v[80:83]
	v_mfma_f32_16x16x32_bf16 v[84:87], v[12:15], v[68:71], v[84:87]
	v_mfma_f32_16x16x32_bf16 v[88:91], v[20:23], v[68:71], v[88:91]
	v_mfma_f32_16x16x32_bf16 v[92:95], v[28:31], v[68:71], v[92:95]
	global_load_dwordx4 v[64:67], v[152:153], off
	global_load_dwordx4 v[68:71], v[152:153], off offset:1024
	v_max_f32_e32 v96, 0, v96
	v_max_f32_e32 v100, 0, v100
	v_max_f32_e32 v104, 0, v104
	v_max_f32_e32 v108, 0, v108
	v_max_f32_e32 v97, 0, v97
	v_max_f32_e32 v101, 0, v101
	v_max_f32_e32 v105, 0, v105
	v_max_f32_e32 v109, 0, v109
	v_max_f32_e32 v98, 0, v98
	v_max_f32_e32 v102, 0, v102
	v_max_f32_e32 v106, 0, v106
	v_max_f32_e32 v110, 0, v110
	v_max_f32_e32 v99, 0, v99
	v_max_f32_e32 v103, 0, v103
	v_max_f32_e32 v107, 0, v107
	v_max_f32_e32 v111, 0, v111
	v_mul_f32_e32 v133, v44, v96
	v_mul_f32_e32 v137, v40, v100
	v_mul_f32_e32 v141, v36, v104
	v_mul_f32_e32 v145, v32, v108
	v_fmac_f32_e32 v133, v45, v97
	v_fmac_f32_e32 v137, v41, v101
	v_fmac_f32_e32 v141, v37, v105
	v_fmac_f32_e32 v145, v33, v109
	v_fmac_f32_e32 v133, v46, v98
	v_fmac_f32_e32 v137, v42, v102
	v_fmac_f32_e32 v141, v38, v106
	v_fmac_f32_e32 v145, v34, v110
	v_fmac_f32_e32 v133, v47, v99
	v_fmac_f32_e32 v137, v43, v103
	v_fmac_f32_e32 v141, v39, v107
	v_fmac_f32_e32 v145, v35, v111
	s_waitcnt vmcnt(6)
	v_mfma_f32_16x16x32_bf16 v[96:99], v[0:3], v[72:75], 0
	v_mfma_f32_16x16x32_bf16 v[100:103], v[8:11], v[72:75], 0
	v_mfma_f32_16x16x32_bf16 v[104:107], v[16:19], v[72:75], 0
	v_mfma_f32_16x16x32_bf16 v[108:111], v[24:27], v[72:75], 0
	v_mfma_f32_16x16x32_bf16 v[96:99], v[4:7], v[76:79], v[96:99]
	v_mfma_f32_16x16x32_bf16 v[100:103], v[12:15], v[76:79], v[100:103]
	v_mfma_f32_16x16x32_bf16 v[104:107], v[20:23], v[76:79], v[104:107]
	v_mfma_f32_16x16x32_bf16 v[108:111], v[28:31], v[76:79], v[108:111]
	global_load_dwordx4 v[72:75], v[152:153], off offset:2048
	global_load_dwordx4 v[76:79], v[152:153], off offset:3072
	v_lshl_add_u64 v[150:151], v[150:151], 0, s[18:19]
	v_lshl_add_u64 v[152:153], v[152:153], 0, s[18:19]
	v_max_f32_e32 v80, 0, v80
	v_max_f32_e32 v84, 0, v84
	v_max_f32_e32 v88, 0, v88
	v_max_f32_e32 v92, 0, v92
	v_max_f32_e32 v81, 0, v81
	v_max_f32_e32 v85, 0, v85
	v_max_f32_e32 v89, 0, v89
	v_max_f32_e32 v93, 0, v93
	v_max_f32_e32 v82, 0, v82
	v_max_f32_e32 v86, 0, v86
	v_max_f32_e32 v90, 0, v90
	v_max_f32_e32 v94, 0, v94
	v_max_f32_e32 v83, 0, v83
	v_max_f32_e32 v87, 0, v87
	v_max_f32_e32 v91, 0, v91
	v_max_f32_e32 v95, 0, v95
	v_mul_f32_e32 v134, v44, v80
	v_mul_f32_e32 v138, v40, v84
	v_mul_f32_e32 v142, v36, v88
	v_mul_f32_e32 v146, v32, v92
	v_fmac_f32_e32 v134, v45, v81
	v_fmac_f32_e32 v138, v41, v85
	v_fmac_f32_e32 v142, v37, v89
	v_fmac_f32_e32 v146, v33, v93
	v_fmac_f32_e32 v134, v46, v82
	v_fmac_f32_e32 v138, v42, v86
	v_fmac_f32_e32 v142, v38, v90
	v_fmac_f32_e32 v146, v34, v94
	v_fmac_f32_e32 v134, v47, v83
	v_fmac_f32_e32 v138, v43, v87
	v_fmac_f32_e32 v142, v39, v91
	v_fmac_f32_e32 v146, v35, v95
	v_max_f32_e32 v96, 0, v96
	v_max_f32_e32 v100, 0, v100
	v_max_f32_e32 v104, 0, v104
	v_max_f32_e32 v108, 0, v108
	v_max_f32_e32 v97, 0, v97
	v_max_f32_e32 v101, 0, v101
	v_max_f32_e32 v105, 0, v105
	v_max_f32_e32 v109, 0, v109
	v_max_f32_e32 v98, 0, v98
	v_max_f32_e32 v102, 0, v102
	v_max_f32_e32 v106, 0, v106
	v_max_f32_e32 v110, 0, v110
	v_max_f32_e32 v99, 0, v99
	v_max_f32_e32 v103, 0, v103
	v_max_f32_e32 v107, 0, v107
	v_max_f32_e32 v111, 0, v111
	v_mul_f32_e32 v135, v44, v96
	v_mul_f32_e32 v139, v40, v100
	v_mul_f32_e32 v143, v36, v104
	v_mul_f32_e32 v147, v32, v108
	v_fmac_f32_e32 v135, v45, v97
	v_fmac_f32_e32 v139, v41, v101
	v_fmac_f32_e32 v143, v37, v105
	v_fmac_f32_e32 v147, v33, v109
	v_fmac_f32_e32 v135, v46, v98
	v_fmac_f32_e32 v139, v42, v102
	v_fmac_f32_e32 v143, v38, v106
	v_fmac_f32_e32 v147, v34, v110
	v_fmac_f32_e32 v135, v47, v99
	v_fmac_f32_e32 v139, v43, v103
	v_fmac_f32_e32 v143, v39, v107
	v_fmac_f32_e32 v147, v35, v111
	s_nop 1
	v_permlane32_swap_b32_e32 v132, v134
	v_permlane32_swap_b32_e32 v133, v135
	v_permlane32_swap_b32_e32 v136, v138
	v_permlane32_swap_b32_e32 v137, v139
	v_permlane32_swap_b32_e32 v140, v142
	v_permlane32_swap_b32_e32 v141, v143
	v_permlane32_swap_b32_e32 v144, v146
	v_permlane32_swap_b32_e32 v145, v147
	v_add_f32_e32 v112, v132, v134
	v_add_f32_e32 v113, v133, v135
	v_add_f32_e32 v114, v136, v138
	v_add_f32_e32 v115, v137, v139
	v_add_f32_e32 v116, v140, v142
	v_add_f32_e32 v117, v141, v143
	v_add_f32_e32 v118, v144, v146
	v_add_f32_e32 v119, v145, v147
	s_nop 1
	v_permlane16_swap_b32_e32 v112, v113
	v_permlane16_swap_b32_e32 v114, v115
	v_permlane16_swap_b32_e32 v116, v117
	v_permlane16_swap_b32_e32 v118, v119
	v_add_u32_e32 v156, 0x800, v130
	v_add_u32_e32 v157, 0x800, v155
	v_add_f32_e32 v120, v112, v113
	v_add_f32_e32 v121, v114, v115
	v_add_f32_e32 v122, v116, v117
	v_add_f32_e32 v123, v118, v119
	v_ashrrev_i32_e32 v112, 31, v120
	v_ashrrev_i32_e32 v113, 31, v121
	v_ashrrev_i32_e32 v114, 31, v122
	v_ashrrev_i32_e32 v115, 31, v123
	v_cmp_le_u32_e32 vcc, v154, v124
	v_cmp_le_u32_e64 s[16:17], v154, v128
	v_cmp_le_u32_e64 s[44:45], v154, v129
	v_cmp_le_u32_e64 s[78:79], v154, v126
	v_or_b32_e32 v112, 0x80000000, v112
	v_or_b32_e32 v113, 0x80000000, v113
	v_or_b32_e32 v114, 0x80000000, v114
	v_or_b32_e32 v115, 0x80000000, v115
	v_xor_b32_e32 v120, v120, v112
	v_xor_b32_e32 v121, v121, v113
	v_xor_b32_e32 v122, v122, v114
	v_xor_b32_e32 v123, v123, v115
	v_cndmask_b32_e32 v120, 0, v120, vcc
	v_cndmask_b32_e64 v121, 0, v121, s[16:17]
	v_cndmask_b32_e64 v122, 0, v122, s[44:45]
	v_cndmask_b32_e64 v123, 0, v123, s[78:79]
	ds_write2st64_b32 v130, v120, v121 offset1:128
	ds_write2st64_b32 v155, v122, v123 offset1:128
	v_mov_b32_e32 v130, v156
	v_mov_b32_e32 v155, v157
	v_add_u32_e32 v154, 0x200, v154
	s_add_i32 s20, s20, 1
	s_cmp_lt_u32 s20, s14
	s_cbranch_scc1 .Lidx_loop
; __device__ __forceinline__ void attn_item(const Ptrs& P, unsigned char* lds, int b, int tq0, int tid) {
;     ...
; #pragma unroll
;         for (int q = 0; q < 4; ++q) { const bf16_t* qp = P.QI + (rowb + tq0 + q) * 1024 + r16 * 64 + 8 * g; Aq[q][0] = *(const bf16x8*)qp; Aq[q][1] = *(const bf16x8*)(qp + 32);
;             wq[q] = *(const f32x4*)(P.WI + (rowb + tq0 + q) * 16 + 4 * g); }
	s_waitcnt vmcnt(0)
	s_cmp_lg_u32 s62, 0
	s_cbranch_scc1 .Lwarm_skip
	v_readlane_b32 s14, v254, 0
	s_nop 3
	s_cmp_gt_u32 s14, 0x7ff
	s_cbranch_scc1 .Lwarm_skip
	s_lshl_b32 s14, s14, 2
	s_sub_u32 s14, 0x1ffc, s14
	s_add_u32 s14, s14, s81
	s_mov_b32 s17, 0
	s_lshl_b32 s16, s14, 11
	v_lshl_add_u64 v[112:113], v[168:169], 0, s[16:17]
	s_add_u32 s16, s16, 0x1000
	v_lshl_add_u64 v[114:115], v[168:169], 0, s[16:17]
	s_lshl_b32 s16, s14, 6
	v_lshl_add_u64 v[116:117], v[170:171], 0, s[16:17]
	global_load_dwordx4 v[158:161], v[112:113], off
	global_load_dwordx4 v[158:161], v[112:113], off offset:64
	global_load_dwordx4 v[158:161], v[112:113], off offset:2048
	global_load_dwordx4 v[158:161], v[112:113], off offset:2112
	global_load_dwordx4 v[158:161], v[114:115], off
	global_load_dwordx4 v[158:161], v[114:115], off offset:64
	global_load_dwordx4 v[158:161], v[114:115], off offset:2048
	global_load_dwordx4 v[158:161], v[114:115], off offset:2112
	global_load_dwordx4 v[158:161], v[116:117], off
	global_load_dwordx4 v[158:161], v[116:117], off offset:64
	global_load_dwordx4 v[158:161], v[116:117], off offset:128
	global_load_dwordx4 v[158:161], v[116:117], off offset:192
.Lwarm_skip:
	s_branch .LBB0_479
	s_nop 0
	s_nop 0
	s_nop 0
	s_nop 0
	s_nop 0
	s_nop 0
	s_nop 0
	s_nop 0

; __device__ __forceinline__ void attn_item(const Ptrs& P, unsigned char* lds, int b, int tq0, int tid) {
;     ...
;         volatile unsigned* xw = (volatile unsigned*)(lds + 147456);
;         const unsigned seq = (xw[32 + w] + 1u) & 0xffu; if (lane == 0) xw[32 + w] = seq;
.LBB0_487:
	s_or_b64 exec, exec, s[12:13]
	s_lshl_b32 s83, s62, 2
	s_add_i32 s12, s83, 0
	s_add_i32 s20, s12, 0x24080
	v_mov_b64_e32 v[64:65], s[20:21]
	s_waitcnt lgkmcnt(0)
	s_barrier
	ds_read_b32 v64, v64
	s_waitcnt lgkmcnt(0)
	s_nop 0
	s_nop 0
	s_nop 0
	s_nop 0
	s_nop 0
	v_add_u32_e32 v64, 1, v64
	v_and_b32_e32 v96, 0xff, v64
	s_and_saveexec_b64 s[12:13], s[4:5]
	s_cbranch_execz .LBB0_489
	v_mov_b64_e32 v[64:65], s[20:21]
	ds_write_b32 v64, v96
	s_waitcnt lgkmcnt(0)

; __device__ __forceinline__ void attn_item(const Ptrs& P, unsigned char* lds, int b, int tq0, int tid) {
;     ...
;     if (tmax < 256 || (DBG & 4)) {
;         for (int i = tid; i < 1024; i += 512) sel[i] = (unsigned short)(((i & 255) <= tq0 + (i >> 8)) ? (i & 255) : 0);
;         __syncthreads();
.LBB0_913:
	s_or_saveexec_b64 s[14:15], s[60:61]
	v_mov_b32_e32 v32, s65
	v_mov_b32_e32 v219, s64
	s_xor_b64 exec, exec, s[14:15]
	s_cbranch_execz .LBB0_921
	s_nop 0
	s_nop 0
	s_nop 0
	s_nop 0
	s_nop 0
	v_sub_u32_e32 v0, v208, v64
	v_sub_u32_e32 v1, v210, v64
	s_mov_b32 s18, 0
	s_mov_b64 s[16:17], 0
	v_mov_b32_e32 v2, v209
	s_branch .LBB0_916
